# back-edge rotation: GEMM K-loop counter/pointer/exit-test SALU moved in front of the loop-back barrier (4 loops)
# speedup vs baseline: 1.0238x; 1.0238x over previous
.LBB0_131:
	ds_read_b128 v[152:155], v148
	ds_read_b128 v[156:159], v148 offset:1024
	ds_read_b128 v[160:163], v148 offset:2048
	ds_read_b128 v[164:167], v148 offset:3072
	ds_read_b128 v[168:171], v149
	ds_read_b128 v[172:175], v149 offset:1024
	ds_read_b128 v[176:179], v149 offset:2048
	ds_read_b128 v[180:183], v149 offset:3072
	s_add_u32 s20, s18, 0xfffc0080
	s_addc_u32 s21, s19, -1
	s_cmp_eq_u32 s46, 12
	s_cselect_b32 s23, s13, s21
	s_cselect_b32 s22, s42, s20
	s_cselect_b32 s21, s11, s45
	s_cselect_b32 s20, s43, s44
	s_add_i32 m0, s9, 0xc000
	ds_read_b128 v[184:187], v150
	ds_read_b128 v[188:191], v150 offset:1024
	ds_read_b128 v[192:195], v150 offset:2048
	ds_read_b128 v[196:199], v150 offset:3072
	ds_read_b128 v[200:203], v150 offset:4096
	ds_read_b128 v[204:207], v150 offset:5120
	ds_read_b128 v[208:211], v150 offset:6144
	ds_read_b128 v[212:215], v150 offset:7168
	global_load_lds_dwordx4 v136, s[18:19]
	s_add_i32 m0, s9, 0xe000
	s_nop 0
	global_load_lds_dwordx4 v138, s[18:19]
	s_waitcnt vmcnt(8)
	s_waitcnt lgkmcnt(0)
	s_barrier
	s_setprio 1
	s_waitcnt lgkmcnt(0)
	v_mfma_f32_16x16x32_bf16 v[124:127], v[152:155], v[184:187], v[124:127]
	v_mfma_f32_16x16x32_bf16 v[120:123], v[160:163], v[184:187], v[120:123]
	v_mfma_f32_16x16x32_bf16 v[116:119], v[152:155], v[192:195], v[116:119]
	v_mfma_f32_16x16x32_bf16 v[112:115], v[160:163], v[192:195], v[112:115]
	v_mfma_f32_16x16x32_bf16 v[100:103], v[152:155], v[200:203], v[100:103]
	v_mfma_f32_16x16x32_bf16 v[96:99], v[160:163], v[200:203], v[96:99]
	v_mfma_f32_16x16x32_bf16 v[84:87], v[152:155], v[208:211], v[84:87]
	v_mfma_f32_16x16x32_bf16 v[80:83], v[160:163], v[208:211], v[80:83]
	v_mfma_f32_16x16x32_bf16 v[124:127], v[156:159], v[188:191], v[124:127]
	v_mfma_f32_16x16x32_bf16 v[120:123], v[164:167], v[188:191], v[120:123]
	v_mfma_f32_16x16x32_bf16 v[116:119], v[156:159], v[196:199], v[116:119]
	v_mfma_f32_16x16x32_bf16 v[112:115], v[164:167], v[196:199], v[112:115]
	v_mfma_f32_16x16x32_bf16 v[100:103], v[156:159], v[204:207], v[100:103]
	v_mfma_f32_16x16x32_bf16 v[96:99], v[164:167], v[204:207], v[96:99]
	v_mfma_f32_16x16x32_bf16 v[84:87], v[156:159], v[212:215], v[84:87]
	v_mfma_f32_16x16x32_bf16 v[80:83], v[164:167], v[212:215], v[80:83]
	s_setprio 0
	s_setprio 1
	v_mfma_f32_16x16x32_bf16 v[108:111], v[168:171], v[184:187], v[108:111]
	v_mfma_f32_16x16x32_bf16 v[104:107], v[176:179], v[184:187], v[104:107]
	v_mfma_f32_16x16x32_bf16 v[92:95], v[168:171], v[192:195], v[92:95]
	v_mfma_f32_16x16x32_bf16 v[88:91], v[176:179], v[192:195], v[88:91]
	v_mfma_f32_16x16x32_bf16 v[76:79], v[168:171], v[200:203], v[76:79]
	v_mfma_f32_16x16x32_bf16 v[72:75], v[176:179], v[200:203], v[72:75]
	v_mfma_f32_16x16x32_bf16 v[68:71], v[168:171], v[208:211], v[68:71]
	v_mfma_f32_16x16x32_bf16 v[64:67], v[176:179], v[208:211], v[64:67]
	v_mfma_f32_16x16x32_bf16 v[108:111], v[172:175], v[188:191], v[108:111]
	v_mfma_f32_16x16x32_bf16 v[104:107], v[180:183], v[188:191], v[104:107]
	v_mfma_f32_16x16x32_bf16 v[92:95], v[172:175], v[196:199], v[92:95]
	v_mfma_f32_16x16x32_bf16 v[88:91], v[180:183], v[196:199], v[88:91]
	v_mfma_f32_16x16x32_bf16 v[76:79], v[172:175], v[204:207], v[76:79]
	v_mfma_f32_16x16x32_bf16 v[72:75], v[180:183], v[204:207], v[72:75]
	v_mfma_f32_16x16x32_bf16 v[68:71], v[172:175], v[212:215], v[68:71]
	v_mfma_f32_16x16x32_bf16 v[64:67], v[180:183], v[212:215], v[64:67]
	s_setprio 0
	s_barrier
	s_add_i32 s47, s38, s26
	s_mov_b32 m0, s47
	ds_read_b128 v[184:187], v150 offset:16384
	ds_read_b128 v[188:191], v150 offset:17408
	ds_read_b128 v[192:195], v150 offset:18432
	ds_read_b128 v[196:199], v150 offset:19456
	ds_read_b128 v[200:203], v150 offset:20480
	ds_read_b128 v[204:207], v150 offset:21504
	ds_read_b128 v[208:211], v150 offset:22528
	ds_read_b128 v[212:215], v150 offset:23552
	global_load_lds_dwordx4 v132, s[20:21]
	s_add_i32 m0, s47, 0x2000
	s_add_u32 s48, s20, 0x40000
	s_addc_u32 s49, s21, 0
	s_add_i32 s47, s39, s26
	global_load_lds_dwordx4 v128, s[20:21]
	s_mov_b32 m0, s47
	s_nop 0
	global_load_lds_dwordx4 v132, s[48:49]
	s_add_i32 m0, s47, 0x2000
	s_nop 0
	global_load_lds_dwordx4 v128, s[48:49]
	s_mov_b32 m0, s9
	s_nop 0
	global_load_lds_dwordx4 v134, s[22:23]
	s_mov_b32 m0, s29
	s_nop 0
	global_load_lds_dwordx4 v130, s[22:23]
	s_add_u32 s84, s20, s4
	s_addc_u32 s85, s21, s5
	s_add_u32 s86, s22, s4
	s_addc_u32 s87, s23, s5
	s_waitcnt vmcnt(8)
	s_waitcnt lgkmcnt(0)
	s_barrier
	s_setprio 1
	s_waitcnt lgkmcnt(0)
	v_mfma_f32_16x16x32_bf16 v[60:63], v[152:155], v[184:187], v[60:63]
	v_mfma_f32_16x16x32_bf16 v[56:59], v[160:163], v[184:187], v[56:59]
	v_mfma_f32_16x16x32_bf16 v[52:55], v[152:155], v[192:195], v[52:55]
	v_mfma_f32_16x16x32_bf16 v[48:51], v[160:163], v[192:195], v[48:51]
	v_mfma_f32_16x16x32_bf16 v[36:39], v[152:155], v[200:203], v[36:39]
	v_mfma_f32_16x16x32_bf16 v[32:35], v[160:163], v[200:203], v[32:35]
	v_mfma_f32_16x16x32_bf16 v[20:23], v[152:155], v[208:211], v[20:23]
	v_mfma_f32_16x16x32_bf16 v[16:19], v[160:163], v[208:211], v[16:19]
	v_mfma_f32_16x16x32_bf16 v[60:63], v[156:159], v[188:191], v[60:63]
	v_mfma_f32_16x16x32_bf16 v[56:59], v[164:167], v[188:191], v[56:59]
	v_mfma_f32_16x16x32_bf16 v[52:55], v[156:159], v[196:199], v[52:55]
	v_mfma_f32_16x16x32_bf16 v[48:51], v[164:167], v[196:199], v[48:51]
	v_mfma_f32_16x16x32_bf16 v[36:39], v[156:159], v[204:207], v[36:39]
	v_mfma_f32_16x16x32_bf16 v[32:35], v[164:167], v[204:207], v[32:35]
	v_mfma_f32_16x16x32_bf16 v[20:23], v[156:159], v[212:215], v[20:23]
	v_mfma_f32_16x16x32_bf16 v[16:19], v[164:167], v[212:215], v[16:19]
	s_setprio 0
	s_setprio 1
	v_mfma_f32_16x16x32_bf16 v[44:47], v[168:171], v[184:187], v[44:47]
	v_mfma_f32_16x16x32_bf16 v[40:43], v[176:179], v[184:187], v[40:43]
	v_mfma_f32_16x16x32_bf16 v[28:31], v[168:171], v[192:195], v[28:31]
	v_mfma_f32_16x16x32_bf16 v[24:27], v[176:179], v[192:195], v[24:27]
	v_mfma_f32_16x16x32_bf16 v[12:15], v[168:171], v[200:203], v[12:15]
	v_mfma_f32_16x16x32_bf16 v[8:11], v[176:179], v[200:203], v[8:11]
	v_mfma_f32_16x16x32_bf16 v[4:7], v[168:171], v[208:211], v[4:7]
	v_mfma_f32_16x16x32_bf16 v[0:3], v[176:179], v[208:211], v[0:3]
	v_mfma_f32_16x16x32_bf16 v[44:47], v[172:175], v[188:191], v[44:47]
	v_mfma_f32_16x16x32_bf16 v[40:43], v[180:183], v[188:191], v[40:43]
	v_mfma_f32_16x16x32_bf16 v[28:31], v[172:175], v[196:199], v[28:31]
	v_mfma_f32_16x16x32_bf16 v[24:27], v[180:183], v[196:199], v[24:27]
	v_mfma_f32_16x16x32_bf16 v[12:15], v[172:175], v[204:207], v[12:15]
	v_mfma_f32_16x16x32_bf16 v[8:11], v[180:183], v[204:207], v[8:11]
	v_mfma_f32_16x16x32_bf16 v[4:7], v[172:175], v[212:215], v[4:7]
	v_mfma_f32_16x16x32_bf16 v[0:3], v[180:183], v[212:215], v[0:3]
	s_setprio 0
	s_barrier
	s_add_i32 s47, 0, 0x18000
	v_add_u32_e32 v151, s47, v146
	s_add_i32 s48, 0, 0x1c000
	ds_read_b128 v[152:155], v151
	ds_read_b128 v[156:159], v151 offset:1024
	ds_read_b128 v[160:163], v151 offset:2048
	ds_read_b128 v[164:167], v151 offset:3072
	v_add_u32_e32 v151, s48, v146
	ds_read_b128 v[168:171], v151
	ds_read_b128 v[172:175], v151 offset:1024
	ds_read_b128 v[176:179], v151 offset:2048
	ds_read_b128 v[180:183], v151 offset:3072
	s_add_u32 s22, s22, 0x40000
	s_addc_u32 s23, s23, 0
	s_mov_b32 m0, s30
	ds_read_b128 v[184:187], v150 offset:32768
	ds_read_b128 v[188:191], v150 offset:33792
	ds_read_b128 v[192:195], v150 offset:34816
	ds_read_b128 v[196:199], v150 offset:35840
	ds_read_b128 v[200:203], v150 offset:36864
	ds_read_b128 v[204:207], v150 offset:37888
	ds_read_b128 v[208:211], v150 offset:38912
	ds_read_b128 v[212:215], v150 offset:39936
	global_load_lds_dwordx4 v134, s[22:23]
	s_mov_b32 m0, s31
	s_nop 0
	global_load_lds_dwordx4 v130, s[22:23]
	s_waitcnt vmcnt(8)
	s_waitcnt lgkmcnt(0)
	s_barrier
	s_setprio 1
	s_waitcnt lgkmcnt(0)
	v_mfma_f32_16x16x32_bf16 v[124:127], v[152:155], v[184:187], v[124:127]
	v_mfma_f32_16x16x32_bf16 v[120:123], v[160:163], v[184:187], v[120:123]
	v_mfma_f32_16x16x32_bf16 v[116:119], v[152:155], v[192:195], v[116:119]
	v_mfma_f32_16x16x32_bf16 v[112:115], v[160:163], v[192:195], v[112:115]
	v_mfma_f32_16x16x32_bf16 v[100:103], v[152:155], v[200:203], v[100:103]
	v_mfma_f32_16x16x32_bf16 v[96:99], v[160:163], v[200:203], v[96:99]
	v_mfma_f32_16x16x32_bf16 v[84:87], v[152:155], v[208:211], v[84:87]
	v_mfma_f32_16x16x32_bf16 v[80:83], v[160:163], v[208:211], v[80:83]
	v_mfma_f32_16x16x32_bf16 v[124:127], v[156:159], v[188:191], v[124:127]
	v_mfma_f32_16x16x32_bf16 v[120:123], v[164:167], v[188:191], v[120:123]
	v_mfma_f32_16x16x32_bf16 v[116:119], v[156:159], v[196:199], v[116:119]
	v_mfma_f32_16x16x32_bf16 v[112:115], v[164:167], v[196:199], v[112:115]
	v_mfma_f32_16x16x32_bf16 v[100:103], v[156:159], v[204:207], v[100:103]
	v_mfma_f32_16x16x32_bf16 v[96:99], v[164:167], v[204:207], v[96:99]
	v_mfma_f32_16x16x32_bf16 v[84:87], v[156:159], v[212:215], v[84:87]
	v_mfma_f32_16x16x32_bf16 v[80:83], v[164:167], v[212:215], v[80:83]
	s_setprio 0
	s_setprio 1
	v_mfma_f32_16x16x32_bf16 v[108:111], v[168:171], v[184:187], v[108:111]
	v_mfma_f32_16x16x32_bf16 v[104:107], v[176:179], v[184:187], v[104:107]
	v_mfma_f32_16x16x32_bf16 v[92:95], v[168:171], v[192:195], v[92:95]
	v_mfma_f32_16x16x32_bf16 v[88:91], v[176:179], v[192:195], v[88:91]
	v_mfma_f32_16x16x32_bf16 v[76:79], v[168:171], v[200:203], v[76:79]
	v_mfma_f32_16x16x32_bf16 v[72:75], v[176:179], v[200:203], v[72:75]
	v_mfma_f32_16x16x32_bf16 v[68:71], v[168:171], v[208:211], v[68:71]
	v_mfma_f32_16x16x32_bf16 v[64:67], v[176:179], v[208:211], v[64:67]
	v_mfma_f32_16x16x32_bf16 v[108:111], v[172:175], v[188:191], v[108:111]
	v_mfma_f32_16x16x32_bf16 v[104:107], v[180:183], v[188:191], v[104:107]
	v_mfma_f32_16x16x32_bf16 v[92:95], v[172:175], v[196:199], v[92:95]
	v_mfma_f32_16x16x32_bf16 v[88:91], v[180:183], v[196:199], v[88:91]
	v_mfma_f32_16x16x32_bf16 v[76:79], v[172:175], v[204:207], v[76:79]
	v_mfma_f32_16x16x32_bf16 v[72:75], v[180:183], v[204:207], v[72:75]
	v_mfma_f32_16x16x32_bf16 v[68:71], v[172:175], v[212:215], v[68:71]
	v_mfma_f32_16x16x32_bf16 v[64:67], v[180:183], v[212:215], v[64:67]
	s_setprio 0
	s_barrier
	s_add_i32 s22, s47, s26
	s_mov_b32 m0, s22
	ds_read_b128 v[184:187], v150 offset:49152
	ds_read_b128 v[188:191], v150 offset:50176
	ds_read_b128 v[192:195], v150 offset:51200
	ds_read_b128 v[196:199], v150 offset:52224
	ds_read_b128 v[200:203], v150 offset:53248
	ds_read_b128 v[204:207], v150 offset:54272
	ds_read_b128 v[208:211], v150 offset:55296
	ds_read_b128 v[212:215], v150 offset:56320
	global_load_lds_dwordx4 v132, s[84:85]
	s_add_i32 m0, s22, 0x2000
	s_add_u32 s20, s20, 0x40080
	s_addc_u32 s21, s21, 0
	s_add_i32 s22, s48, s26
	global_load_lds_dwordx4 v128, s[84:85]
	s_mov_b32 m0, s22
	s_nop 0
	global_load_lds_dwordx4 v132, s[20:21]
	s_add_i32 m0, s22, 0x2000
	s_nop 0
	global_load_lds_dwordx4 v128, s[20:21]
	s_mov_b32 m0, s34
	s_nop 0
	global_load_lds_dwordx4 v134, s[86:87]
	s_mov_b32 m0, s35
	s_nop 0
	global_load_lds_dwordx4 v130, s[86:87]
	s_waitcnt vmcnt(8)
	s_waitcnt lgkmcnt(0)
	s_barrier
	s_setprio 1
	s_waitcnt lgkmcnt(0)
	v_mfma_f32_16x16x32_bf16 v[60:63], v[152:155], v[184:187], v[60:63]
	v_mfma_f32_16x16x32_bf16 v[56:59], v[160:163], v[184:187], v[56:59]
	v_mfma_f32_16x16x32_bf16 v[52:55], v[152:155], v[192:195], v[52:55]
	v_mfma_f32_16x16x32_bf16 v[48:51], v[160:163], v[192:195], v[48:51]
	v_mfma_f32_16x16x32_bf16 v[36:39], v[152:155], v[200:203], v[36:39]
	v_mfma_f32_16x16x32_bf16 v[32:35], v[160:163], v[200:203], v[32:35]
	v_mfma_f32_16x16x32_bf16 v[20:23], v[152:155], v[208:211], v[20:23]
	v_mfma_f32_16x16x32_bf16 v[16:19], v[160:163], v[208:211], v[16:19]
	v_mfma_f32_16x16x32_bf16 v[60:63], v[156:159], v[188:191], v[60:63]
	v_mfma_f32_16x16x32_bf16 v[56:59], v[164:167], v[188:191], v[56:59]
	v_mfma_f32_16x16x32_bf16 v[52:55], v[156:159], v[196:199], v[52:55]
	v_mfma_f32_16x16x32_bf16 v[48:51], v[164:167], v[196:199], v[48:51]
	v_mfma_f32_16x16x32_bf16 v[36:39], v[156:159], v[204:207], v[36:39]
	v_mfma_f32_16x16x32_bf16 v[32:35], v[164:167], v[204:207], v[32:35]
	v_mfma_f32_16x16x32_bf16 v[20:23], v[156:159], v[212:215], v[20:23]
	v_mfma_f32_16x16x32_bf16 v[16:19], v[164:167], v[212:215], v[16:19]
	s_setprio 0
	s_setprio 1
	v_mfma_f32_16x16x32_bf16 v[44:47], v[168:171], v[184:187], v[44:47]
	v_mfma_f32_16x16x32_bf16 v[40:43], v[176:179], v[184:187], v[40:43]
	v_mfma_f32_16x16x32_bf16 v[28:31], v[168:171], v[192:195], v[28:31]
	v_mfma_f32_16x16x32_bf16 v[24:27], v[176:179], v[192:195], v[24:27]
	v_mfma_f32_16x16x32_bf16 v[12:15], v[168:171], v[200:203], v[12:15]
	v_mfma_f32_16x16x32_bf16 v[8:11], v[176:179], v[200:203], v[8:11]
	v_mfma_f32_16x16x32_bf16 v[4:7], v[168:171], v[208:211], v[4:7]
	v_mfma_f32_16x16x32_bf16 v[0:3], v[176:179], v[208:211], v[0:3]
	v_mfma_f32_16x16x32_bf16 v[44:47], v[172:175], v[188:191], v[44:47]
	v_mfma_f32_16x16x32_bf16 v[40:43], v[180:183], v[188:191], v[40:43]
	v_mfma_f32_16x16x32_bf16 v[28:31], v[172:175], v[196:199], v[28:31]
	v_mfma_f32_16x16x32_bf16 v[24:27], v[180:183], v[196:199], v[24:27]
	v_mfma_f32_16x16x32_bf16 v[12:15], v[172:175], v[204:207], v[12:15]
	v_mfma_f32_16x16x32_bf16 v[8:11], v[180:183], v[204:207], v[8:11]
	v_mfma_f32_16x16x32_bf16 v[4:7], v[172:175], v[212:215], v[4:7]
	v_mfma_f32_16x16x32_bf16 v[0:3], v[180:183], v[212:215], v[0:3]
	s_setprio 0
	s_add_i32 s46, s46, 2
	s_add_u32 s18, s18, 0x100
	s_addc_u32 s19, s19, 0
	s_add_u32 s44, s44, 0x100
	s_addc_u32 s45, s45, 0
	s_cmp_gt_u32 s46, 13
	s_barrier


	s_cbranch_scc0 .LBB0_131
	s_and_b64 vcc, exec, s[6:7]
	s_cbranch_vccz .LBB0_134
	s_barrier

.LBB0_365:
	s_add_u32 s10, s60, s8
	s_addc_u32 s11, s61, s9
	s_add_u32 s10, s10, 0x5dc0100
	s_addc_u32 s11, s11, 0
	s_add_u32 s65, s62, s8
	s_addc_u32 s66, s63, s9
	s_add_i32 s67, 0, 0x10000
	s_cmpk_eq_i32 s8, 0x700
	s_cselect_b32 s27, s7, s11
	s_cselect_b32 s26, s6, s10
	s_cselect_b32 s11, s1, s66
	s_cselect_b32 s10, s0, s65
	s_add_i32 s65, 0, 0x14000
	v_add_u32_e32 v144, s67, v122
	v_add_u32_e32 v165, s65, v122
	ds_read_b128 v[124:127], v144
	ds_read_b128 v[128:131], v144 offset:1024
	ds_read_b128 v[132:135], v144 offset:2048
	ds_read_b128 v[144:147], v144 offset:3072
	ds_read_b128 v[148:151], v165
	ds_read_b128 v[160:163], v165 offset:1024
	ds_read_b128 v[166:169], v165 offset:2048
	ds_read_b128 v[170:173], v165 offset:3072
	v_lshl_add_u64 v[206:207], v[110:111], 0, s[8:9]
	s_add_i32 m0, s23, 0xc000
	ds_read_b128 v[174:177], v123
	ds_read_b128 v[178:181], v123 offset:1024
	ds_read_b128 v[182:185], v123 offset:2048
	ds_read_b128 v[186:189], v123 offset:3072
	ds_read_b128 v[190:193], v123 offset:4096
	ds_read_b128 v[194:197], v123 offset:5120
	ds_read_b128 v[198:201], v123 offset:6144
	ds_read_b128 v[202:205], v123 offset:7168
	global_load_lds_dwordx4 v[206:207], off
	v_lshl_add_u64 v[206:207], v[120:121], 0, s[8:9]
	s_add_i32 m0, s23, 0xe000
	s_nop 0
	global_load_lds_dwordx4 v[206:207], off
	s_waitcnt vmcnt(8)
	s_waitcnt lgkmcnt(0)
	s_barrier
	s_setprio 1
	s_waitcnt lgkmcnt(0)
	v_mfma_f32_16x16x32_bf16 v[156:159], v[124:127], v[174:177], v[156:159]
	v_mfma_f32_16x16x32_bf16 v[152:155], v[132:135], v[174:177], v[152:155]
	v_mfma_f32_16x16x32_bf16 v[116:119], v[124:127], v[182:185], v[116:119]
	v_mfma_f32_16x16x32_bf16 v[112:115], v[132:135], v[182:185], v[112:115]
	v_mfma_f32_16x16x32_bf16 v[92:95], v[124:127], v[190:193], v[92:95]
	v_mfma_f32_16x16x32_bf16 v[88:91], v[132:135], v[190:193], v[88:91]
	v_mfma_f32_16x16x32_bf16 v[76:79], v[124:127], v[198:201], v[76:79]
	v_mfma_f32_16x16x32_bf16 v[72:75], v[132:135], v[198:201], v[72:75]
	v_mfma_f32_16x16x32_bf16 v[156:159], v[128:131], v[178:181], v[156:159]
	v_mfma_f32_16x16x32_bf16 v[152:155], v[144:147], v[178:181], v[152:155]
	v_mfma_f32_16x16x32_bf16 v[116:119], v[128:131], v[186:189], v[116:119]
	v_mfma_f32_16x16x32_bf16 v[112:115], v[144:147], v[186:189], v[112:115]
	v_mfma_f32_16x16x32_bf16 v[92:95], v[128:131], v[194:197], v[92:95]
	v_mfma_f32_16x16x32_bf16 v[88:91], v[144:147], v[194:197], v[88:91]
	v_mfma_f32_16x16x32_bf16 v[76:79], v[128:131], v[202:205], v[76:79]
	v_mfma_f32_16x16x32_bf16 v[72:75], v[144:147], v[202:205], v[72:75]
	s_setprio 0
	s_setprio 1
	v_mfma_f32_16x16x32_bf16 v[140:143], v[148:151], v[174:177], v[140:143]
	v_mfma_f32_16x16x32_bf16 v[136:139], v[166:169], v[174:177], v[136:139]
	v_mfma_f32_16x16x32_bf16 v[104:107], v[148:151], v[182:185], v[104:107]
	v_mfma_f32_16x16x32_bf16 v[96:99], v[166:169], v[182:185], v[96:99]
	v_mfma_f32_16x16x32_bf16 v[84:87], v[148:151], v[190:193], v[84:87]
	v_mfma_f32_16x16x32_bf16 v[80:83], v[166:169], v[190:193], v[80:83]
	v_mfma_f32_16x16x32_bf16 v[68:71], v[148:151], v[198:201], v[68:71]
	v_mfma_f32_16x16x32_bf16 v[64:67], v[166:169], v[198:201], v[64:67]
	v_mfma_f32_16x16x32_bf16 v[140:143], v[160:163], v[178:181], v[140:143]
	v_mfma_f32_16x16x32_bf16 v[136:139], v[170:173], v[178:181], v[136:139]
	v_mfma_f32_16x16x32_bf16 v[104:107], v[160:163], v[186:189], v[104:107]
	v_mfma_f32_16x16x32_bf16 v[96:99], v[170:173], v[186:189], v[96:99]
	v_mfma_f32_16x16x32_bf16 v[84:87], v[160:163], v[194:197], v[84:87]
	v_mfma_f32_16x16x32_bf16 v[80:83], v[170:173], v[194:197], v[80:83]
	v_mfma_f32_16x16x32_bf16 v[68:71], v[160:163], v[202:205], v[68:71]
	v_mfma_f32_16x16x32_bf16 v[64:67], v[170:173], v[202:205], v[64:67]
	s_setprio 0
	s_barrier
	s_add_i32 s66, s67, s48
	s_mov_b32 m0, s66
	ds_read_b128 v[174:177], v123 offset:16384
	ds_read_b128 v[178:181], v123 offset:17408
	ds_read_b128 v[182:185], v123 offset:18432
	ds_read_b128 v[186:189], v123 offset:19456
	ds_read_b128 v[190:193], v123 offset:20480
	ds_read_b128 v[194:197], v123 offset:21504
	ds_read_b128 v[198:201], v123 offset:22528
	ds_read_b128 v[202:205], v123 offset:23552
	global_load_lds_dwordx4 v212, s[10:11]
	s_add_i32 m0, s66, 0x2000
	s_add_u32 s66, s10, 0x40000
	s_addc_u32 s67, s11, 0
	s_add_i32 s65, s65, s48
	global_load_lds_dwordx4 v100, s[10:11]
	s_mov_b32 m0, s65
	s_nop 0
	global_load_lds_dwordx4 v212, s[66:67]
	s_add_i32 m0, s65, 0x2000
	s_nop 0
	global_load_lds_dwordx4 v100, s[66:67]
	s_mov_b32 m0, s23
	s_nop 0
	global_load_lds_dwordx4 v108, s[26:27]
	s_mov_b32 m0, s49
	s_nop 0
	global_load_lds_dwordx4 v102, s[26:27]
	s_add_u32 s86, s26, s34
	s_addc_u32 s87, s27, s35
	s_add_u32 s84, s10, s34
	s_addc_u32 s85, s11, s35
	s_waitcnt vmcnt(8)
	s_waitcnt lgkmcnt(0)
	s_barrier
	s_setprio 1
	s_waitcnt lgkmcnt(0)
	v_mfma_f32_16x16x32_bf16 v[60:63], v[124:127], v[174:177], v[60:63]
	v_mfma_f32_16x16x32_bf16 v[56:59], v[132:135], v[174:177], v[56:59]
	v_mfma_f32_16x16x32_bf16 v[44:47], v[124:127], v[182:185], v[44:47]
	v_mfma_f32_16x16x32_bf16 v[40:43], v[132:135], v[182:185], v[40:43]
	v_mfma_f32_16x16x32_bf16 v[28:31], v[124:127], v[190:193], v[28:31]
	v_mfma_f32_16x16x32_bf16 v[24:27], v[132:135], v[190:193], v[24:27]
	v_mfma_f32_16x16x32_bf16 v[12:15], v[124:127], v[198:201], v[12:15]
	v_mfma_f32_16x16x32_bf16 v[8:11], v[132:135], v[198:201], v[8:11]
	v_mfma_f32_16x16x32_bf16 v[60:63], v[128:131], v[178:181], v[60:63]
	v_mfma_f32_16x16x32_bf16 v[56:59], v[144:147], v[178:181], v[56:59]
	v_mfma_f32_16x16x32_bf16 v[44:47], v[128:131], v[186:189], v[44:47]
	v_mfma_f32_16x16x32_bf16 v[40:43], v[144:147], v[186:189], v[40:43]
	v_mfma_f32_16x16x32_bf16 v[28:31], v[128:131], v[194:197], v[28:31]
	v_mfma_f32_16x16x32_bf16 v[24:27], v[144:147], v[194:197], v[24:27]
	v_mfma_f32_16x16x32_bf16 v[12:15], v[128:131], v[202:205], v[12:15]
	v_mfma_f32_16x16x32_bf16 v[8:11], v[144:147], v[202:205], v[8:11]
	s_setprio 0
	s_setprio 1
	v_mfma_f32_16x16x32_bf16 v[52:55], v[148:151], v[174:177], v[52:55]
	v_mfma_f32_16x16x32_bf16 v[48:51], v[166:169], v[174:177], v[48:51]
	v_mfma_f32_16x16x32_bf16 v[36:39], v[148:151], v[182:185], v[36:39]
	v_mfma_f32_16x16x32_bf16 v[32:35], v[166:169], v[182:185], v[32:35]
	v_mfma_f32_16x16x32_bf16 v[20:23], v[148:151], v[190:193], v[20:23]
	v_mfma_f32_16x16x32_bf16 v[16:19], v[166:169], v[190:193], v[16:19]
	v_mfma_f32_16x16x32_bf16 v[4:7], v[148:151], v[198:201], v[4:7]
	v_mfma_f32_16x16x32_bf16 v[0:3], v[166:169], v[198:201], v[0:3]
	v_mfma_f32_16x16x32_bf16 v[52:55], v[160:163], v[178:181], v[52:55]
	v_mfma_f32_16x16x32_bf16 v[48:51], v[170:173], v[178:181], v[48:51]
	v_mfma_f32_16x16x32_bf16 v[36:39], v[160:163], v[186:189], v[36:39]
	v_mfma_f32_16x16x32_bf16 v[32:35], v[170:173], v[186:189], v[32:35]
	v_mfma_f32_16x16x32_bf16 v[20:23], v[160:163], v[194:197], v[20:23]
	v_mfma_f32_16x16x32_bf16 v[16:19], v[170:173], v[194:197], v[16:19]
	v_mfma_f32_16x16x32_bf16 v[4:7], v[160:163], v[202:205], v[4:7]
	v_mfma_f32_16x16x32_bf16 v[0:3], v[170:173], v[202:205], v[0:3]
	s_setprio 0
	s_barrier
	s_add_i32 s65, 0, 0x18000
	s_add_i32 s66, 0, 0x1c000
	v_add_u32_e32 v144, s65, v122
	v_add_u32_e32 v165, s66, v122
	ds_read_b128 v[124:127], v144
	ds_read_b128 v[128:131], v144 offset:1024
	ds_read_b128 v[132:135], v144 offset:2048
	ds_read_b128 v[144:147], v144 offset:3072
	ds_read_b128 v[148:151], v165
	ds_read_b128 v[160:163], v165 offset:1024
	ds_read_b128 v[166:169], v165 offset:2048
	ds_read_b128 v[170:173], v165 offset:3072
	s_add_u32 s26, s26, 0x40000
	s_addc_u32 s27, s27, 0
	s_mov_b32 m0, s50
	ds_read_b128 v[174:177], v123 offset:32768
	ds_read_b128 v[178:181], v123 offset:33792
	ds_read_b128 v[182:185], v123 offset:34816
	ds_read_b128 v[186:189], v123 offset:35840
	ds_read_b128 v[190:193], v123 offset:36864
	ds_read_b128 v[194:197], v123 offset:37888
	ds_read_b128 v[198:201], v123 offset:38912
	ds_read_b128 v[202:205], v123 offset:39936
	global_load_lds_dwordx4 v108, s[26:27]
	s_mov_b32 m0, s51
	s_nop 0
	global_load_lds_dwordx4 v102, s[26:27]
	s_waitcnt vmcnt(8)
	s_waitcnt lgkmcnt(0)
	s_barrier
	s_setprio 1
	s_waitcnt lgkmcnt(0)
	v_mfma_f32_16x16x32_bf16 v[156:159], v[124:127], v[174:177], v[156:159]
	v_mfma_f32_16x16x32_bf16 v[152:155], v[132:135], v[174:177], v[152:155]
	v_mfma_f32_16x16x32_bf16 v[116:119], v[124:127], v[182:185], v[116:119]
	v_mfma_f32_16x16x32_bf16 v[112:115], v[132:135], v[182:185], v[112:115]
	v_mfma_f32_16x16x32_bf16 v[92:95], v[124:127], v[190:193], v[92:95]
	v_mfma_f32_16x16x32_bf16 v[88:91], v[132:135], v[190:193], v[88:91]
	v_mfma_f32_16x16x32_bf16 v[76:79], v[124:127], v[198:201], v[76:79]
	v_mfma_f32_16x16x32_bf16 v[72:75], v[132:135], v[198:201], v[72:75]
	v_mfma_f32_16x16x32_bf16 v[156:159], v[128:131], v[178:181], v[156:159]
	v_mfma_f32_16x16x32_bf16 v[152:155], v[144:147], v[178:181], v[152:155]
	v_mfma_f32_16x16x32_bf16 v[116:119], v[128:131], v[186:189], v[116:119]
	v_mfma_f32_16x16x32_bf16 v[112:115], v[144:147], v[186:189], v[112:115]
	v_mfma_f32_16x16x32_bf16 v[92:95], v[128:131], v[194:197], v[92:95]
	v_mfma_f32_16x16x32_bf16 v[88:91], v[144:147], v[194:197], v[88:91]
	v_mfma_f32_16x16x32_bf16 v[76:79], v[128:131], v[202:205], v[76:79]
	v_mfma_f32_16x16x32_bf16 v[72:75], v[144:147], v[202:205], v[72:75]
	s_setprio 0
	s_setprio 1
	v_mfma_f32_16x16x32_bf16 v[140:143], v[148:151], v[174:177], v[140:143]
	v_mfma_f32_16x16x32_bf16 v[136:139], v[166:169], v[174:177], v[136:139]
	v_mfma_f32_16x16x32_bf16 v[104:107], v[148:151], v[182:185], v[104:107]
	v_mfma_f32_16x16x32_bf16 v[96:99], v[166:169], v[182:185], v[96:99]
	v_mfma_f32_16x16x32_bf16 v[84:87], v[148:151], v[190:193], v[84:87]
	v_mfma_f32_16x16x32_bf16 v[80:83], v[166:169], v[190:193], v[80:83]
	v_mfma_f32_16x16x32_bf16 v[68:71], v[148:151], v[198:201], v[68:71]
	v_mfma_f32_16x16x32_bf16 v[64:67], v[166:169], v[198:201], v[64:67]
	v_mfma_f32_16x16x32_bf16 v[140:143], v[160:163], v[178:181], v[140:143]
	v_mfma_f32_16x16x32_bf16 v[136:139], v[170:173], v[178:181], v[136:139]
	v_mfma_f32_16x16x32_bf16 v[104:107], v[160:163], v[186:189], v[104:107]
	v_mfma_f32_16x16x32_bf16 v[96:99], v[170:173], v[186:189], v[96:99]
	v_mfma_f32_16x16x32_bf16 v[84:87], v[160:163], v[194:197], v[84:87]
	v_mfma_f32_16x16x32_bf16 v[80:83], v[170:173], v[194:197], v[80:83]
	v_mfma_f32_16x16x32_bf16 v[68:71], v[160:163], v[202:205], v[68:71]
	v_mfma_f32_16x16x32_bf16 v[64:67], v[170:173], v[202:205], v[64:67]
	s_setprio 0
	s_barrier
	s_add_i32 s26, s65, s48
	s_mov_b32 m0, s26
	ds_read_b128 v[174:177], v123 offset:49152
	ds_read_b128 v[178:181], v123 offset:50176
	ds_read_b128 v[182:185], v123 offset:51200
	ds_read_b128 v[186:189], v123 offset:52224
	ds_read_b128 v[190:193], v123 offset:53248
	ds_read_b128 v[194:197], v123 offset:54272
	ds_read_b128 v[198:201], v123 offset:55296
	ds_read_b128 v[202:205], v123 offset:56320
	global_load_lds_dwordx4 v212, s[84:85]
	s_add_i32 m0, s26, 0x2000
	s_add_u32 s10, s10, 0x40080
	s_addc_u32 s11, s11, 0
	s_add_i32 s26, s66, s48
	global_load_lds_dwordx4 v100, s[84:85]
	s_mov_b32 m0, s26
	s_nop 0
	global_load_lds_dwordx4 v212, s[10:11]
	s_add_i32 m0, s26, 0x2000
	s_nop 0
	global_load_lds_dwordx4 v100, s[10:11]
	s_mov_b32 m0, s58
	s_nop 0
	global_load_lds_dwordx4 v108, s[86:87]
	s_mov_b32 m0, s59
	s_nop 0
	global_load_lds_dwordx4 v102, s[86:87]
	s_waitcnt vmcnt(8)
	s_waitcnt lgkmcnt(0)
	s_barrier
	s_setprio 1
	s_waitcnt lgkmcnt(0)
	v_mfma_f32_16x16x32_bf16 v[60:63], v[124:127], v[174:177], v[60:63]
	v_mfma_f32_16x16x32_bf16 v[56:59], v[132:135], v[174:177], v[56:59]
	v_mfma_f32_16x16x32_bf16 v[44:47], v[124:127], v[182:185], v[44:47]
	v_mfma_f32_16x16x32_bf16 v[40:43], v[132:135], v[182:185], v[40:43]
	v_mfma_f32_16x16x32_bf16 v[28:31], v[124:127], v[190:193], v[28:31]
	v_mfma_f32_16x16x32_bf16 v[24:27], v[132:135], v[190:193], v[24:27]
	v_mfma_f32_16x16x32_bf16 v[12:15], v[124:127], v[198:201], v[12:15]
	v_mfma_f32_16x16x32_bf16 v[8:11], v[132:135], v[198:201], v[8:11]
	v_mfma_f32_16x16x32_bf16 v[60:63], v[128:131], v[178:181], v[60:63]
	v_mfma_f32_16x16x32_bf16 v[56:59], v[144:147], v[178:181], v[56:59]
	v_mfma_f32_16x16x32_bf16 v[44:47], v[128:131], v[186:189], v[44:47]
	v_mfma_f32_16x16x32_bf16 v[40:43], v[144:147], v[186:189], v[40:43]
	v_mfma_f32_16x16x32_bf16 v[28:31], v[128:131], v[194:197], v[28:31]
	v_mfma_f32_16x16x32_bf16 v[24:27], v[144:147], v[194:197], v[24:27]
	v_mfma_f32_16x16x32_bf16 v[12:15], v[128:131], v[202:205], v[12:15]
	v_mfma_f32_16x16x32_bf16 v[8:11], v[144:147], v[202:205], v[8:11]
	s_setprio 0
	s_setprio 1
	v_mfma_f32_16x16x32_bf16 v[52:55], v[148:151], v[174:177], v[52:55]
	v_mfma_f32_16x16x32_bf16 v[48:51], v[166:169], v[174:177], v[48:51]
	v_mfma_f32_16x16x32_bf16 v[36:39], v[148:151], v[182:185], v[36:39]
	v_mfma_f32_16x16x32_bf16 v[32:35], v[166:169], v[182:185], v[32:35]
	v_mfma_f32_16x16x32_bf16 v[20:23], v[148:151], v[190:193], v[20:23]
	v_mfma_f32_16x16x32_bf16 v[16:19], v[166:169], v[190:193], v[16:19]
	v_mfma_f32_16x16x32_bf16 v[4:7], v[148:151], v[198:201], v[4:7]
	v_mfma_f32_16x16x32_bf16 v[0:3], v[166:169], v[198:201], v[0:3]
	v_mfma_f32_16x16x32_bf16 v[52:55], v[160:163], v[178:181], v[52:55]
	v_mfma_f32_16x16x32_bf16 v[48:51], v[170:173], v[178:181], v[48:51]
	v_mfma_f32_16x16x32_bf16 v[36:39], v[160:163], v[186:189], v[36:39]
	v_mfma_f32_16x16x32_bf16 v[32:35], v[170:173], v[186:189], v[32:35]
	v_mfma_f32_16x16x32_bf16 v[20:23], v[160:163], v[194:197], v[20:23]
	v_mfma_f32_16x16x32_bf16 v[16:19], v[170:173], v[194:197], v[16:19]
	v_mfma_f32_16x16x32_bf16 v[4:7], v[160:163], v[202:205], v[4:7]
	v_mfma_f32_16x16x32_bf16 v[0:3], v[170:173], v[202:205], v[0:3]
	s_setprio 0
	s_add_i32 s64, s64, 2
	s_add_u32 s8, s8, 0x100
	s_addc_u32 s9, s9, 0
	s_cmp_lt_u32 s64, 14
	s_barrier


	s_cbranch_scc1 .LBB0_365
	s_waitcnt vmcnt(0)
	s_cmpk_gt_u32 s47, 0xff
	s_cbranch_scc1 .LBB0_368
	s_barrier

.LBB0_498:
	v_add_u32_e32 v188, s46, v165
	v_add_u32_e32 v204, s47, v165
	ds_read_b128 v[176:179], v188
	ds_read_b128 v[180:183], v188 offset:1024
	ds_read_b128 v[184:187], v188 offset:2048
	ds_read_b128 v[188:191], v188 offset:3072
	ds_read_b128 v[192:195], v204
	ds_read_b128 v[196:199], v204 offset:1024
	ds_read_b128 v[200:203], v204 offset:2048
	ds_read_b128 v[204:207], v204 offset:3072
	s_add_u32 s30, s26, 0xfffc0080
	s_addc_u32 s31, s27, -1
	s_and_b64 s[28:29], s[28:29], exec
	s_cselect_b32 s31, s11, s31
	s_cselect_b32 s30, s49, s30
	s_cselect_b32 s29, s9, s52
	s_cselect_b32 s28, s50, s51
	s_add_i32 m0, s36, 0xc000
	ds_read_b128 v[208:211], v167
	ds_read_b128 v[212:215], v167 offset:1024
	ds_read_b128 v[216:219], v167 offset:2048
	ds_read_b128 v[220:223], v167 offset:3072
	ds_read_b128 v[224:227], v167 offset:4096
	ds_read_b128 v[230:233], v167 offset:5120
	ds_read_b128 v[234:237], v167 offset:6144
	ds_read_b128 v[238:241], v167 offset:7168
	global_load_lds_dwordx4 v136, s[26:27]
	s_add_i32 m0, s36, 0xe000
	s_nop 0
	global_load_lds_dwordx4 v138, s[26:27]
	s_waitcnt vmcnt(8)
	s_waitcnt lgkmcnt(0)
	s_barrier
	s_setprio 1
	s_waitcnt lgkmcnt(0)
	v_mfma_f32_16x16x32_bf16 v[124:127], v[176:179], v[208:211], v[124:127]
	v_mfma_f32_16x16x32_bf16 v[120:123], v[184:187], v[208:211], v[120:123]
	v_mfma_f32_16x16x32_bf16 v[108:111], v[176:179], v[216:219], v[108:111]
	v_mfma_f32_16x16x32_bf16 v[104:107], v[184:187], v[216:219], v[104:107]
	v_mfma_f32_16x16x32_bf16 v[92:95], v[176:179], v[224:227], v[92:95]
	v_mfma_f32_16x16x32_bf16 v[88:91], v[184:187], v[224:227], v[88:91]
	v_mfma_f32_16x16x32_bf16 v[76:79], v[176:179], v[234:237], v[76:79]
	v_mfma_f32_16x16x32_bf16 v[72:75], v[184:187], v[234:237], v[72:75]
	v_mfma_f32_16x16x32_bf16 v[124:127], v[180:183], v[212:215], v[124:127]
	v_mfma_f32_16x16x32_bf16 v[120:123], v[188:191], v[212:215], v[120:123]
	v_mfma_f32_16x16x32_bf16 v[108:111], v[180:183], v[220:223], v[108:111]
	v_mfma_f32_16x16x32_bf16 v[104:107], v[188:191], v[220:223], v[104:107]
	v_mfma_f32_16x16x32_bf16 v[92:95], v[180:183], v[230:233], v[92:95]
	v_mfma_f32_16x16x32_bf16 v[88:91], v[188:191], v[230:233], v[88:91]
	v_mfma_f32_16x16x32_bf16 v[76:79], v[180:183], v[238:241], v[76:79]
	v_mfma_f32_16x16x32_bf16 v[72:75], v[188:191], v[238:241], v[72:75]
	s_setprio 0
	s_setprio 1
	v_mfma_f32_16x16x32_bf16 v[116:119], v[192:195], v[208:211], v[116:119]
	v_mfma_f32_16x16x32_bf16 v[112:115], v[200:203], v[208:211], v[112:115]
	v_mfma_f32_16x16x32_bf16 v[100:103], v[192:195], v[216:219], v[100:103]
	v_mfma_f32_16x16x32_bf16 v[96:99], v[200:203], v[216:219], v[96:99]
	v_mfma_f32_16x16x32_bf16 v[84:87], v[192:195], v[224:227], v[84:87]
	v_mfma_f32_16x16x32_bf16 v[80:83], v[200:203], v[224:227], v[80:83]
	v_mfma_f32_16x16x32_bf16 v[68:71], v[192:195], v[234:237], v[68:71]
	v_mfma_f32_16x16x32_bf16 v[64:67], v[200:203], v[234:237], v[64:67]
	v_mfma_f32_16x16x32_bf16 v[116:119], v[196:199], v[212:215], v[116:119]
	v_mfma_f32_16x16x32_bf16 v[112:115], v[204:207], v[212:215], v[112:115]
	v_mfma_f32_16x16x32_bf16 v[100:103], v[196:199], v[220:223], v[100:103]
	v_mfma_f32_16x16x32_bf16 v[96:99], v[204:207], v[220:223], v[96:99]
	v_mfma_f32_16x16x32_bf16 v[84:87], v[196:199], v[230:233], v[84:87]
	v_mfma_f32_16x16x32_bf16 v[80:83], v[204:207], v[230:233], v[80:83]
	v_mfma_f32_16x16x32_bf16 v[68:71], v[196:199], v[238:241], v[68:71]
	v_mfma_f32_16x16x32_bf16 v[64:67], v[204:207], v[238:241], v[64:67]
	s_setprio 0
	s_barrier
	s_add_i32 s54, s46, s35
	s_mov_b32 m0, s54
	ds_read_b128 v[208:211], v167 offset:16384
	ds_read_b128 v[212:215], v167 offset:17408
	ds_read_b128 v[216:219], v167 offset:18432
	ds_read_b128 v[220:223], v167 offset:19456
	ds_read_b128 v[224:227], v167 offset:20480
	ds_read_b128 v[230:233], v167 offset:21504
	ds_read_b128 v[234:237], v167 offset:22528
	ds_read_b128 v[238:241], v167 offset:23552
	global_load_lds_dwordx4 v130, s[28:29]
	s_add_i32 m0, s54, 0x2000
	s_add_u32 s54, s28, 0x40000
	s_addc_u32 s55, s29, 0
	s_add_i32 s56, s47, s35
	global_load_lds_dwordx4 v134, s[28:29]
	s_mov_b32 m0, s56
	s_nop 0
	global_load_lds_dwordx4 v130, s[54:55]
	s_add_i32 m0, s56, 0x2000
	s_nop 0
	global_load_lds_dwordx4 v134, s[54:55]
	s_mov_b32 m0, s36
	s_nop 0
	global_load_lds_dwordx4 v128, s[30:31]
	s_mov_b32 m0, s37
	s_nop 0
	global_load_lds_dwordx4 v132, s[30:31]
	s_add_u32 s86, s30, s4
	s_addc_u32 s87, s31, s5
	s_add_u32 s84, s28, s4
	s_addc_u32 s85, s29, s5
	s_waitcnt vmcnt(8)
	s_waitcnt lgkmcnt(0)
	s_barrier
	s_setprio 1
	s_waitcnt lgkmcnt(0)
	v_mfma_f32_16x16x32_bf16 v[60:63], v[176:179], v[208:211], v[60:63]
	v_mfma_f32_16x16x32_bf16 v[56:59], v[184:187], v[208:211], v[56:59]
	v_mfma_f32_16x16x32_bf16 v[44:47], v[176:179], v[216:219], v[44:47]
	v_mfma_f32_16x16x32_bf16 v[40:43], v[184:187], v[216:219], v[40:43]
	v_mfma_f32_16x16x32_bf16 v[28:31], v[176:179], v[224:227], v[28:31]
	v_mfma_f32_16x16x32_bf16 v[24:27], v[184:187], v[224:227], v[24:27]
	v_mfma_f32_16x16x32_bf16 v[12:15], v[176:179], v[234:237], v[12:15]
	v_mfma_f32_16x16x32_bf16 v[8:11], v[184:187], v[234:237], v[8:11]
	v_mfma_f32_16x16x32_bf16 v[60:63], v[180:183], v[212:215], v[60:63]
	v_mfma_f32_16x16x32_bf16 v[56:59], v[188:191], v[212:215], v[56:59]
	v_mfma_f32_16x16x32_bf16 v[44:47], v[180:183], v[220:223], v[44:47]
	v_mfma_f32_16x16x32_bf16 v[40:43], v[188:191], v[220:223], v[40:43]
	v_mfma_f32_16x16x32_bf16 v[28:31], v[180:183], v[230:233], v[28:31]
	v_mfma_f32_16x16x32_bf16 v[24:27], v[188:191], v[230:233], v[24:27]
	v_mfma_f32_16x16x32_bf16 v[12:15], v[180:183], v[238:241], v[12:15]
	v_mfma_f32_16x16x32_bf16 v[8:11], v[188:191], v[238:241], v[8:11]
	s_setprio 0
	s_setprio 1
	v_mfma_f32_16x16x32_bf16 v[52:55], v[192:195], v[208:211], v[52:55]
	v_mfma_f32_16x16x32_bf16 v[48:51], v[200:203], v[208:211], v[48:51]
	v_mfma_f32_16x16x32_bf16 v[36:39], v[192:195], v[216:219], v[36:39]
	v_mfma_f32_16x16x32_bf16 v[32:35], v[200:203], v[216:219], v[32:35]
	v_mfma_f32_16x16x32_bf16 v[20:23], v[192:195], v[224:227], v[20:23]
	v_mfma_f32_16x16x32_bf16 v[16:19], v[200:203], v[224:227], v[16:19]
	v_mfma_f32_16x16x32_bf16 v[4:7], v[192:195], v[234:237], v[4:7]
	v_mfma_f32_16x16x32_bf16 v[0:3], v[200:203], v[234:237], v[0:3]
	v_mfma_f32_16x16x32_bf16 v[52:55], v[196:199], v[212:215], v[52:55]
	v_mfma_f32_16x16x32_bf16 v[48:51], v[204:207], v[212:215], v[48:51]
	v_mfma_f32_16x16x32_bf16 v[36:39], v[196:199], v[220:223], v[36:39]
	v_mfma_f32_16x16x32_bf16 v[32:35], v[204:207], v[220:223], v[32:35]
	v_mfma_f32_16x16x32_bf16 v[20:23], v[196:199], v[230:233], v[20:23]
	v_mfma_f32_16x16x32_bf16 v[16:19], v[204:207], v[230:233], v[16:19]
	v_mfma_f32_16x16x32_bf16 v[4:7], v[196:199], v[238:241], v[4:7]
	v_mfma_f32_16x16x32_bf16 v[0:3], v[204:207], v[238:241], v[0:3]
	s_setprio 0
	s_barrier
	s_add_i32 s54, 0, 0x18000
	s_add_i32 s55, 0, 0x1c000
	v_add_u32_e32 v188, s54, v165
	v_add_u32_e32 v204, s55, v165
	ds_read_b128 v[176:179], v188
	ds_read_b128 v[180:183], v188 offset:1024
	ds_read_b128 v[184:187], v188 offset:2048
	ds_read_b128 v[188:191], v188 offset:3072
	ds_read_b128 v[192:195], v204
	ds_read_b128 v[196:199], v204 offset:1024
	ds_read_b128 v[200:203], v204 offset:2048
	ds_read_b128 v[204:207], v204 offset:3072
	s_add_u32 s30, s30, 0x40000
	s_addc_u32 s31, s31, 0
	s_mov_b32 m0, s41
	ds_read_b128 v[208:211], v167 offset:32768
	ds_read_b128 v[212:215], v167 offset:33792
	ds_read_b128 v[216:219], v167 offset:34816
	ds_read_b128 v[220:223], v167 offset:35840
	ds_read_b128 v[224:227], v167 offset:36864
	ds_read_b128 v[230:233], v167 offset:37888
	ds_read_b128 v[234:237], v167 offset:38912
	ds_read_b128 v[238:241], v167 offset:39936
	global_load_lds_dwordx4 v128, s[30:31]
	s_mov_b32 m0, s42
	s_nop 0
	global_load_lds_dwordx4 v132, s[30:31]
	s_waitcnt vmcnt(8)
	s_waitcnt lgkmcnt(0)
	s_barrier
	s_setprio 1
	s_waitcnt lgkmcnt(0)
	v_mfma_f32_16x16x32_bf16 v[124:127], v[176:179], v[208:211], v[124:127]
	v_mfma_f32_16x16x32_bf16 v[120:123], v[184:187], v[208:211], v[120:123]
	v_mfma_f32_16x16x32_bf16 v[108:111], v[176:179], v[216:219], v[108:111]
	v_mfma_f32_16x16x32_bf16 v[104:107], v[184:187], v[216:219], v[104:107]
	v_mfma_f32_16x16x32_bf16 v[92:95], v[176:179], v[224:227], v[92:95]
	v_mfma_f32_16x16x32_bf16 v[88:91], v[184:187], v[224:227], v[88:91]
	v_mfma_f32_16x16x32_bf16 v[76:79], v[176:179], v[234:237], v[76:79]
	v_mfma_f32_16x16x32_bf16 v[72:75], v[184:187], v[234:237], v[72:75]
	v_mfma_f32_16x16x32_bf16 v[124:127], v[180:183], v[212:215], v[124:127]
	v_mfma_f32_16x16x32_bf16 v[120:123], v[188:191], v[212:215], v[120:123]
	v_mfma_f32_16x16x32_bf16 v[108:111], v[180:183], v[220:223], v[108:111]
	v_mfma_f32_16x16x32_bf16 v[104:107], v[188:191], v[220:223], v[104:107]
	v_mfma_f32_16x16x32_bf16 v[92:95], v[180:183], v[230:233], v[92:95]
	v_mfma_f32_16x16x32_bf16 v[88:91], v[188:191], v[230:233], v[88:91]
	v_mfma_f32_16x16x32_bf16 v[76:79], v[180:183], v[238:241], v[76:79]
	v_mfma_f32_16x16x32_bf16 v[72:75], v[188:191], v[238:241], v[72:75]
	s_setprio 0
	s_setprio 1
	v_mfma_f32_16x16x32_bf16 v[116:119], v[192:195], v[208:211], v[116:119]
	v_mfma_f32_16x16x32_bf16 v[112:115], v[200:203], v[208:211], v[112:115]
	v_mfma_f32_16x16x32_bf16 v[100:103], v[192:195], v[216:219], v[100:103]
	v_mfma_f32_16x16x32_bf16 v[96:99], v[200:203], v[216:219], v[96:99]
	v_mfma_f32_16x16x32_bf16 v[84:87], v[192:195], v[224:227], v[84:87]
	v_mfma_f32_16x16x32_bf16 v[80:83], v[200:203], v[224:227], v[80:83]
	v_mfma_f32_16x16x32_bf16 v[68:71], v[192:195], v[234:237], v[68:71]
	v_mfma_f32_16x16x32_bf16 v[64:67], v[200:203], v[234:237], v[64:67]
	v_mfma_f32_16x16x32_bf16 v[116:119], v[196:199], v[212:215], v[116:119]
	v_mfma_f32_16x16x32_bf16 v[112:115], v[204:207], v[212:215], v[112:115]
	v_mfma_f32_16x16x32_bf16 v[100:103], v[196:199], v[220:223], v[100:103]
	v_mfma_f32_16x16x32_bf16 v[96:99], v[204:207], v[220:223], v[96:99]
	v_mfma_f32_16x16x32_bf16 v[84:87], v[196:199], v[230:233], v[84:87]
	v_mfma_f32_16x16x32_bf16 v[80:83], v[204:207], v[230:233], v[80:83]
	v_mfma_f32_16x16x32_bf16 v[68:71], v[196:199], v[238:241], v[68:71]
	v_mfma_f32_16x16x32_bf16 v[64:67], v[204:207], v[238:241], v[64:67]
	s_setprio 0
	s_barrier
	s_add_i32 s30, s54, s35
	s_mov_b32 m0, s30
	ds_read_b128 v[208:211], v167 offset:49152
	ds_read_b128 v[212:215], v167 offset:50176
	ds_read_b128 v[216:219], v167 offset:51200
	ds_read_b128 v[220:223], v167 offset:52224
	ds_read_b128 v[224:227], v167 offset:53248
	ds_read_b128 v[230:233], v167 offset:54272
	ds_read_b128 v[234:237], v167 offset:55296
	ds_read_b128 v[238:241], v167 offset:56320
	global_load_lds_dwordx4 v130, s[84:85]
	s_add_i32 m0, s30, 0x2000
	s_add_u32 s28, s28, 0x40080
	s_addc_u32 s29, s29, 0
	s_add_i32 s30, s55, s35
	global_load_lds_dwordx4 v134, s[84:85]
	s_mov_b32 m0, s30
	s_nop 0
	global_load_lds_dwordx4 v130, s[28:29]
	s_add_i32 m0, s30, 0x2000
	s_nop 0
	global_load_lds_dwordx4 v134, s[28:29]
	s_mov_b32 m0, s44
	s_nop 0
	global_load_lds_dwordx4 v128, s[86:87]
	s_mov_b32 m0, s45
	s_nop 0
	global_load_lds_dwordx4 v132, s[86:87]
	s_waitcnt vmcnt(8)
	s_waitcnt lgkmcnt(0)
	s_barrier
	s_setprio 1
	s_waitcnt lgkmcnt(0)
	v_mfma_f32_16x16x32_bf16 v[60:63], v[176:179], v[208:211], v[60:63]
	v_mfma_f32_16x16x32_bf16 v[56:59], v[184:187], v[208:211], v[56:59]
	v_mfma_f32_16x16x32_bf16 v[44:47], v[176:179], v[216:219], v[44:47]
	v_mfma_f32_16x16x32_bf16 v[40:43], v[184:187], v[216:219], v[40:43]
	v_mfma_f32_16x16x32_bf16 v[28:31], v[176:179], v[224:227], v[28:31]
	v_mfma_f32_16x16x32_bf16 v[24:27], v[184:187], v[224:227], v[24:27]
	v_mfma_f32_16x16x32_bf16 v[12:15], v[176:179], v[234:237], v[12:15]
	v_mfma_f32_16x16x32_bf16 v[8:11], v[184:187], v[234:237], v[8:11]
	v_mfma_f32_16x16x32_bf16 v[60:63], v[180:183], v[212:215], v[60:63]
	v_mfma_f32_16x16x32_bf16 v[56:59], v[188:191], v[212:215], v[56:59]
	v_mfma_f32_16x16x32_bf16 v[44:47], v[180:183], v[220:223], v[44:47]
	v_mfma_f32_16x16x32_bf16 v[40:43], v[188:191], v[220:223], v[40:43]
	v_mfma_f32_16x16x32_bf16 v[28:31], v[180:183], v[230:233], v[28:31]
	v_mfma_f32_16x16x32_bf16 v[24:27], v[188:191], v[230:233], v[24:27]
	v_mfma_f32_16x16x32_bf16 v[12:15], v[180:183], v[238:241], v[12:15]
	v_mfma_f32_16x16x32_bf16 v[8:11], v[188:191], v[238:241], v[8:11]
	s_setprio 0
	s_setprio 1
	v_mfma_f32_16x16x32_bf16 v[52:55], v[192:195], v[208:211], v[52:55]
	v_mfma_f32_16x16x32_bf16 v[48:51], v[200:203], v[208:211], v[48:51]
	v_mfma_f32_16x16x32_bf16 v[36:39], v[192:195], v[216:219], v[36:39]
	v_mfma_f32_16x16x32_bf16 v[32:35], v[200:203], v[216:219], v[32:35]
	v_mfma_f32_16x16x32_bf16 v[20:23], v[192:195], v[224:227], v[20:23]
	v_mfma_f32_16x16x32_bf16 v[16:19], v[200:203], v[224:227], v[16:19]
	v_mfma_f32_16x16x32_bf16 v[4:7], v[192:195], v[234:237], v[4:7]
	v_mfma_f32_16x16x32_bf16 v[0:3], v[200:203], v[234:237], v[0:3]
	v_mfma_f32_16x16x32_bf16 v[52:55], v[196:199], v[212:215], v[52:55]
	v_mfma_f32_16x16x32_bf16 v[48:51], v[204:207], v[212:215], v[48:51]
	v_mfma_f32_16x16x32_bf16 v[36:39], v[196:199], v[220:223], v[36:39]
	v_mfma_f32_16x16x32_bf16 v[32:35], v[204:207], v[220:223], v[32:35]
	v_mfma_f32_16x16x32_bf16 v[20:23], v[196:199], v[230:233], v[20:23]
	v_mfma_f32_16x16x32_bf16 v[16:19], v[204:207], v[230:233], v[16:19]
	v_mfma_f32_16x16x32_bf16 v[4:7], v[196:199], v[238:241], v[4:7]
	v_mfma_f32_16x16x32_bf16 v[0:3], v[204:207], v[238:241], v[0:3]
	s_setprio 0
	s_add_i32 s53, s53, 2
	s_add_u32 s26, s26, 0x100
	s_addc_u32 s27, s27, 0
	s_add_u32 s51, s51, 0x100
	s_addc_u32 s52, s52, 0
	s_cmp_gt_u32 s53, 13
	s_barrier


	s_cbranch_scc1 .LBB0_501

.LBB0_599:
	s_add_u32 s20, s50, s18
	s_addc_u32 s21, s51, s19
	s_add_u32 s20, s20, 0x1d80100
	s_addc_u32 s21, s21, 0
	s_add_u32 s55, s52, s18
	s_addc_u32 s56, s53, s19
	s_add_i32 s57, 0, 0x10000
	s_cmpk_eq_i32 s18, 0x1f00
	s_cselect_b32 s23, s11, s21
	s_cselect_b32 s22, s10, s20
	s_cselect_b32 s21, s1, s56
	s_cselect_b32 s20, s0, s55
	s_add_i32 s55, 0, 0x14000
	v_add_u32_e32 v152, s57, v138
	v_add_u32_e32 v168, s55, v138
	ds_read_b128 v[140:143], v152
	ds_read_b128 v[144:147], v152 offset:1024
	ds_read_b128 v[148:151], v152 offset:2048
	ds_read_b128 v[152:155], v152 offset:3072
	ds_read_b128 v[156:159], v168
	ds_read_b128 v[160:163], v168 offset:1024
	ds_read_b128 v[164:167], v168 offset:2048
	ds_read_b128 v[168:171], v168 offset:3072
	v_lshl_add_u64 v[180:181], v[134:135], 0, s[18:19]
	s_add_i32 m0, s43, 0xc000
	ds_read_b128 v[172:175], v139
	ds_read_b128 v[176:179], v139 offset:1024
	ds_read_b128 v[184:187], v139 offset:2048
	ds_read_b128 v[188:191], v139 offset:3072
	ds_read_b128 v[192:195], v139 offset:4096
	ds_read_b128 v[196:199], v139 offset:5120
	ds_read_b128 v[200:203], v139 offset:6144
	ds_read_b128 v[204:207], v139 offset:7168
	global_load_lds_dwordx4 v[180:181], off
	v_lshl_add_u64 v[180:181], v[136:137], 0, s[18:19]
	s_add_i32 m0, s43, 0xe000
	s_nop 0
	global_load_lds_dwordx4 v[180:181], off
	s_waitcnt vmcnt(8)
	s_waitcnt lgkmcnt(0)
	s_barrier
	s_setprio 1
	s_waitcnt lgkmcnt(0)
	v_mfma_f32_16x16x32_bf16 v[124:127], v[140:143], v[172:175], v[124:127]
	v_mfma_f32_16x16x32_bf16 v[120:123], v[148:151], v[172:175], v[120:123]
	v_mfma_f32_16x16x32_bf16 v[116:119], v[140:143], v[184:187], v[116:119]
	v_mfma_f32_16x16x32_bf16 v[112:115], v[148:151], v[184:187], v[112:115]
	v_mfma_f32_16x16x32_bf16 v[92:95], v[140:143], v[192:195], v[92:95]
	v_mfma_f32_16x16x32_bf16 v[88:91], v[148:151], v[192:195], v[88:91]
	v_mfma_f32_16x16x32_bf16 v[80:83], v[140:143], v[200:203], v[80:83]
	v_mfma_f32_16x16x32_bf16 v[72:75], v[148:151], v[200:203], v[72:75]
	v_mfma_f32_16x16x32_bf16 v[124:127], v[144:147], v[176:179], v[124:127]
	v_mfma_f32_16x16x32_bf16 v[120:123], v[152:155], v[176:179], v[120:123]
	v_mfma_f32_16x16x32_bf16 v[116:119], v[144:147], v[188:191], v[116:119]
	v_mfma_f32_16x16x32_bf16 v[112:115], v[152:155], v[188:191], v[112:115]
	v_mfma_f32_16x16x32_bf16 v[92:95], v[144:147], v[196:199], v[92:95]
	v_mfma_f32_16x16x32_bf16 v[88:91], v[152:155], v[196:199], v[88:91]
	v_mfma_f32_16x16x32_bf16 v[80:83], v[144:147], v[204:207], v[80:83]
	v_mfma_f32_16x16x32_bf16 v[72:75], v[152:155], v[204:207], v[72:75]
	s_setprio 0
	s_setprio 1
	v_mfma_f32_16x16x32_bf16 v[108:111], v[156:159], v[172:175], v[108:111]
	v_mfma_f32_16x16x32_bf16 v[104:107], v[164:167], v[172:175], v[104:107]
	v_mfma_f32_16x16x32_bf16 v[100:103], v[156:159], v[184:187], v[100:103]
	v_mfma_f32_16x16x32_bf16 v[96:99], v[164:167], v[184:187], v[96:99]
	v_mfma_f32_16x16x32_bf16 v[84:87], v[156:159], v[192:195], v[84:87]
	v_mfma_f32_16x16x32_bf16 v[76:79], v[164:167], v[192:195], v[76:79]
	v_mfma_f32_16x16x32_bf16 v[68:71], v[156:159], v[200:203], v[68:71]
	v_mfma_f32_16x16x32_bf16 v[64:67], v[164:167], v[200:203], v[64:67]
	v_mfma_f32_16x16x32_bf16 v[108:111], v[160:163], v[176:179], v[108:111]
	v_mfma_f32_16x16x32_bf16 v[104:107], v[168:171], v[176:179], v[104:107]
	v_mfma_f32_16x16x32_bf16 v[100:103], v[160:163], v[188:191], v[100:103]
	v_mfma_f32_16x16x32_bf16 v[96:99], v[168:171], v[188:191], v[96:99]
	v_mfma_f32_16x16x32_bf16 v[84:87], v[160:163], v[196:199], v[84:87]
	v_mfma_f32_16x16x32_bf16 v[76:79], v[168:171], v[196:199], v[76:79]
	v_mfma_f32_16x16x32_bf16 v[68:71], v[160:163], v[204:207], v[68:71]
	v_mfma_f32_16x16x32_bf16 v[64:67], v[168:171], v[204:207], v[64:67]
	s_setprio 0
	s_barrier
	s_add_i32 s56, s57, s42
	s_mov_b32 m0, s56
	ds_read_b128 v[172:175], v139 offset:16384
	ds_read_b128 v[176:179], v139 offset:17408
	ds_read_b128 v[184:187], v139 offset:18432
	ds_read_b128 v[188:191], v139 offset:19456
	ds_read_b128 v[192:195], v139 offset:20480
	ds_read_b128 v[196:199], v139 offset:21504
	ds_read_b128 v[200:203], v139 offset:22528
	ds_read_b128 v[204:207], v139 offset:23552
	global_load_lds_dwordx4 v212, s[20:21]
	s_add_i32 m0, s56, 0x2000
	s_add_u32 s56, s20, 0x100000
	s_addc_u32 s57, s21, 0
	s_add_i32 s55, s55, s42
	global_load_lds_dwordx4 v128, s[20:21]
	s_mov_b32 m0, s55
	s_nop 0
	global_load_lds_dwordx4 v212, s[56:57]
	s_add_i32 m0, s55, 0x2000
	s_nop 0
	global_load_lds_dwordx4 v128, s[56:57]
	s_mov_b32 m0, s43
	s_nop 0
	global_load_lds_dwordx4 v132, s[22:23]
	s_mov_b32 m0, s44
	s_nop 0
	global_load_lds_dwordx4 v130, s[22:23]
	s_add_u32 s86, s22, s4
	s_addc_u32 s87, s23, s5
	s_add_u32 s84, s20, s4
	s_addc_u32 s85, s21, s5
	s_waitcnt vmcnt(8)
	s_waitcnt lgkmcnt(0)
	s_barrier
	s_setprio 1
	s_waitcnt lgkmcnt(0)
	v_mfma_f32_16x16x32_bf16 v[60:63], v[140:143], v[172:175], v[60:63]
	v_mfma_f32_16x16x32_bf16 v[56:59], v[148:151], v[172:175], v[56:59]
	v_mfma_f32_16x16x32_bf16 v[48:51], v[140:143], v[184:187], v[48:51]
	v_mfma_f32_16x16x32_bf16 v[40:43], v[148:151], v[184:187], v[40:43]
	v_mfma_f32_16x16x32_bf16 v[28:31], v[140:143], v[192:195], v[28:31]
	v_mfma_f32_16x16x32_bf16 v[24:27], v[148:151], v[192:195], v[24:27]
	v_mfma_f32_16x16x32_bf16 v[16:19], v[140:143], v[200:203], v[16:19]
	v_mfma_f32_16x16x32_bf16 v[8:11], v[148:151], v[200:203], v[8:11]
	v_mfma_f32_16x16x32_bf16 v[60:63], v[144:147], v[176:179], v[60:63]
	v_mfma_f32_16x16x32_bf16 v[56:59], v[152:155], v[176:179], v[56:59]
	v_mfma_f32_16x16x32_bf16 v[48:51], v[144:147], v[188:191], v[48:51]
	v_mfma_f32_16x16x32_bf16 v[40:43], v[152:155], v[188:191], v[40:43]
	v_mfma_f32_16x16x32_bf16 v[28:31], v[144:147], v[196:199], v[28:31]
	v_mfma_f32_16x16x32_bf16 v[24:27], v[152:155], v[196:199], v[24:27]
	v_mfma_f32_16x16x32_bf16 v[16:19], v[144:147], v[204:207], v[16:19]
	v_mfma_f32_16x16x32_bf16 v[8:11], v[152:155], v[204:207], v[8:11]
	s_setprio 0
	s_setprio 1
	v_mfma_f32_16x16x32_bf16 v[52:55], v[156:159], v[172:175], v[52:55]
	v_mfma_f32_16x16x32_bf16 v[44:47], v[164:167], v[172:175], v[44:47]
	v_mfma_f32_16x16x32_bf16 v[36:39], v[156:159], v[184:187], v[36:39]
	v_mfma_f32_16x16x32_bf16 v[32:35], v[164:167], v[184:187], v[32:35]
	v_mfma_f32_16x16x32_bf16 v[20:23], v[156:159], v[192:195], v[20:23]
	v_mfma_f32_16x16x32_bf16 v[12:15], v[164:167], v[192:195], v[12:15]
	v_mfma_f32_16x16x32_bf16 v[4:7], v[156:159], v[200:203], v[4:7]
	v_mfma_f32_16x16x32_bf16 v[0:3], v[164:167], v[200:203], v[0:3]
	v_mfma_f32_16x16x32_bf16 v[52:55], v[160:163], v[176:179], v[52:55]
	v_mfma_f32_16x16x32_bf16 v[44:47], v[168:171], v[176:179], v[44:47]
	v_mfma_f32_16x16x32_bf16 v[36:39], v[160:163], v[188:191], v[36:39]
	v_mfma_f32_16x16x32_bf16 v[32:35], v[168:171], v[188:191], v[32:35]
	v_mfma_f32_16x16x32_bf16 v[20:23], v[160:163], v[196:199], v[20:23]
	v_mfma_f32_16x16x32_bf16 v[12:15], v[168:171], v[196:199], v[12:15]
	v_mfma_f32_16x16x32_bf16 v[4:7], v[160:163], v[204:207], v[4:7]
	v_mfma_f32_16x16x32_bf16 v[0:3], v[168:171], v[204:207], v[0:3]
	s_setprio 0
	s_barrier
	s_add_i32 s55, 0, 0x18000
	s_add_i32 s56, 0, 0x1c000
	v_add_u32_e32 v152, s55, v138
	v_add_u32_e32 v168, s56, v138
	ds_read_b128 v[140:143], v152
	ds_read_b128 v[144:147], v152 offset:1024
	ds_read_b128 v[148:151], v152 offset:2048
	ds_read_b128 v[152:155], v152 offset:3072
	ds_read_b128 v[156:159], v168
	ds_read_b128 v[160:163], v168 offset:1024
	ds_read_b128 v[164:167], v168 offset:2048
	ds_read_b128 v[168:171], v168 offset:3072
	s_add_u32 s22, s22, 0x100000
	s_addc_u32 s23, s23, 0
	s_mov_b32 m0, s45
	ds_read_b128 v[172:175], v139 offset:32768
	ds_read_b128 v[176:179], v139 offset:33792
	ds_read_b128 v[184:187], v139 offset:34816
	ds_read_b128 v[188:191], v139 offset:35840
	ds_read_b128 v[192:195], v139 offset:36864
	ds_read_b128 v[196:199], v139 offset:37888
	ds_read_b128 v[200:203], v139 offset:38912
	ds_read_b128 v[204:207], v139 offset:39936
	global_load_lds_dwordx4 v132, s[22:23]
	s_mov_b32 m0, s46
	s_nop 0
	global_load_lds_dwordx4 v130, s[22:23]
	s_waitcnt vmcnt(8)
	s_waitcnt lgkmcnt(0)
	s_barrier
	s_setprio 1
	s_waitcnt lgkmcnt(0)
	v_mfma_f32_16x16x32_bf16 v[124:127], v[140:143], v[172:175], v[124:127]
	v_mfma_f32_16x16x32_bf16 v[120:123], v[148:151], v[172:175], v[120:123]
	v_mfma_f32_16x16x32_bf16 v[116:119], v[140:143], v[184:187], v[116:119]
	v_mfma_f32_16x16x32_bf16 v[112:115], v[148:151], v[184:187], v[112:115]
	v_mfma_f32_16x16x32_bf16 v[92:95], v[140:143], v[192:195], v[92:95]
	v_mfma_f32_16x16x32_bf16 v[88:91], v[148:151], v[192:195], v[88:91]
	v_mfma_f32_16x16x32_bf16 v[80:83], v[140:143], v[200:203], v[80:83]
	v_mfma_f32_16x16x32_bf16 v[72:75], v[148:151], v[200:203], v[72:75]
	v_mfma_f32_16x16x32_bf16 v[124:127], v[144:147], v[176:179], v[124:127]
	v_mfma_f32_16x16x32_bf16 v[120:123], v[152:155], v[176:179], v[120:123]
	v_mfma_f32_16x16x32_bf16 v[116:119], v[144:147], v[188:191], v[116:119]
	v_mfma_f32_16x16x32_bf16 v[112:115], v[152:155], v[188:191], v[112:115]
	v_mfma_f32_16x16x32_bf16 v[92:95], v[144:147], v[196:199], v[92:95]
	v_mfma_f32_16x16x32_bf16 v[88:91], v[152:155], v[196:199], v[88:91]
	v_mfma_f32_16x16x32_bf16 v[80:83], v[144:147], v[204:207], v[80:83]
	v_mfma_f32_16x16x32_bf16 v[72:75], v[152:155], v[204:207], v[72:75]
	s_setprio 0
	s_setprio 1
	v_mfma_f32_16x16x32_bf16 v[108:111], v[156:159], v[172:175], v[108:111]
	v_mfma_f32_16x16x32_bf16 v[104:107], v[164:167], v[172:175], v[104:107]
	v_mfma_f32_16x16x32_bf16 v[100:103], v[156:159], v[184:187], v[100:103]
	v_mfma_f32_16x16x32_bf16 v[96:99], v[164:167], v[184:187], v[96:99]
	v_mfma_f32_16x16x32_bf16 v[84:87], v[156:159], v[192:195], v[84:87]
	v_mfma_f32_16x16x32_bf16 v[76:79], v[164:167], v[192:195], v[76:79]
	v_mfma_f32_16x16x32_bf16 v[68:71], v[156:159], v[200:203], v[68:71]
	v_mfma_f32_16x16x32_bf16 v[64:67], v[164:167], v[200:203], v[64:67]
	v_mfma_f32_16x16x32_bf16 v[108:111], v[160:163], v[176:179], v[108:111]
	v_mfma_f32_16x16x32_bf16 v[104:107], v[168:171], v[176:179], v[104:107]
	v_mfma_f32_16x16x32_bf16 v[100:103], v[160:163], v[188:191], v[100:103]
	v_mfma_f32_16x16x32_bf16 v[96:99], v[168:171], v[188:191], v[96:99]
	v_mfma_f32_16x16x32_bf16 v[84:87], v[160:163], v[196:199], v[84:87]
	v_mfma_f32_16x16x32_bf16 v[76:79], v[168:171], v[196:199], v[76:79]
	v_mfma_f32_16x16x32_bf16 v[68:71], v[160:163], v[204:207], v[68:71]
	v_mfma_f32_16x16x32_bf16 v[64:67], v[168:171], v[204:207], v[64:67]
	s_setprio 0
	s_barrier
	s_add_i32 s22, s55, s42
	s_mov_b32 m0, s22
	ds_read_b128 v[172:175], v139 offset:49152
	ds_read_b128 v[176:179], v139 offset:50176
	ds_read_b128 v[184:187], v139 offset:51200
	ds_read_b128 v[188:191], v139 offset:52224
	ds_read_b128 v[192:195], v139 offset:53248
	ds_read_b128 v[196:199], v139 offset:54272
	ds_read_b128 v[200:203], v139 offset:55296
	ds_read_b128 v[204:207], v139 offset:56320
	global_load_lds_dwordx4 v212, s[84:85]
	s_add_i32 m0, s22, 0x2000
	s_add_u32 s20, s20, 0x100080
	s_addc_u32 s21, s21, 0
	s_add_i32 s22, s56, s42
	global_load_lds_dwordx4 v128, s[84:85]
	s_mov_b32 m0, s22
	s_nop 0
	global_load_lds_dwordx4 v212, s[20:21]
	s_add_i32 m0, s22, 0x2000
	s_nop 0
	global_load_lds_dwordx4 v128, s[20:21]
	s_mov_b32 m0, s48
	s_nop 0
	global_load_lds_dwordx4 v132, s[86:87]
	s_mov_b32 m0, s49
	s_nop 0
	global_load_lds_dwordx4 v130, s[86:87]
	s_waitcnt vmcnt(8)
	s_waitcnt lgkmcnt(0)
	s_barrier
	s_setprio 1
	s_waitcnt lgkmcnt(0)
	v_mfma_f32_16x16x32_bf16 v[60:63], v[140:143], v[172:175], v[60:63]
	v_mfma_f32_16x16x32_bf16 v[56:59], v[148:151], v[172:175], v[56:59]
	v_mfma_f32_16x16x32_bf16 v[48:51], v[140:143], v[184:187], v[48:51]
	v_mfma_f32_16x16x32_bf16 v[40:43], v[148:151], v[184:187], v[40:43]
	v_mfma_f32_16x16x32_bf16 v[28:31], v[140:143], v[192:195], v[28:31]
	v_mfma_f32_16x16x32_bf16 v[24:27], v[148:151], v[192:195], v[24:27]
	v_mfma_f32_16x16x32_bf16 v[16:19], v[140:143], v[200:203], v[16:19]
	v_mfma_f32_16x16x32_bf16 v[8:11], v[148:151], v[200:203], v[8:11]
	v_mfma_f32_16x16x32_bf16 v[60:63], v[144:147], v[176:179], v[60:63]
	v_mfma_f32_16x16x32_bf16 v[56:59], v[152:155], v[176:179], v[56:59]
	v_mfma_f32_16x16x32_bf16 v[48:51], v[144:147], v[188:191], v[48:51]
	v_mfma_f32_16x16x32_bf16 v[40:43], v[152:155], v[188:191], v[40:43]
	v_mfma_f32_16x16x32_bf16 v[28:31], v[144:147], v[196:199], v[28:31]
	v_mfma_f32_16x16x32_bf16 v[24:27], v[152:155], v[196:199], v[24:27]
	v_mfma_f32_16x16x32_bf16 v[16:19], v[144:147], v[204:207], v[16:19]
	v_mfma_f32_16x16x32_bf16 v[8:11], v[152:155], v[204:207], v[8:11]
	s_setprio 0
	s_setprio 1
	v_mfma_f32_16x16x32_bf16 v[52:55], v[156:159], v[172:175], v[52:55]
	v_mfma_f32_16x16x32_bf16 v[44:47], v[164:167], v[172:175], v[44:47]
	v_mfma_f32_16x16x32_bf16 v[36:39], v[156:159], v[184:187], v[36:39]
	v_mfma_f32_16x16x32_bf16 v[32:35], v[164:167], v[184:187], v[32:35]
	v_mfma_f32_16x16x32_bf16 v[20:23], v[156:159], v[192:195], v[20:23]
	v_mfma_f32_16x16x32_bf16 v[12:15], v[164:167], v[192:195], v[12:15]
	v_mfma_f32_16x16x32_bf16 v[4:7], v[156:159], v[200:203], v[4:7]
	v_mfma_f32_16x16x32_bf16 v[0:3], v[164:167], v[200:203], v[0:3]
	v_mfma_f32_16x16x32_bf16 v[52:55], v[160:163], v[176:179], v[52:55]
	v_mfma_f32_16x16x32_bf16 v[44:47], v[168:171], v[176:179], v[44:47]
	v_mfma_f32_16x16x32_bf16 v[36:39], v[160:163], v[188:191], v[36:39]
	v_mfma_f32_16x16x32_bf16 v[32:35], v[168:171], v[188:191], v[32:35]
	v_mfma_f32_16x16x32_bf16 v[20:23], v[160:163], v[196:199], v[20:23]
	v_mfma_f32_16x16x32_bf16 v[12:15], v[168:171], v[196:199], v[12:15]
	v_mfma_f32_16x16x32_bf16 v[4:7], v[160:163], v[204:207], v[4:7]
	v_mfma_f32_16x16x32_bf16 v[0:3], v[168:171], v[204:207], v[0:3]
	s_setprio 0
	s_add_i32 s54, s54, 2
	s_add_u32 s18, s18, 0x100
	s_addc_u32 s19, s19, 0
	s_cmp_lt_u32 s54, 62
	s_barrier


	s_cbranch_scc1 .LBB0_599
	s_waitcnt vmcnt(0)
	s_cmpk_gt_u32 s36, 0xff
	s_cbranch_scc1 .LBB0_602
	s_barrier
